# GEMM ring K-loop: LDS fragment reads for the next ks interleaved between the MFMAs (ks=1,2 blocks)
# speedup vs baseline: 1.1708x; 1.0068x over previous
.Lgr1_loop:
	s_add_u32 s51, s50, 0x10000
	s_sub_u32 s53, s51, 0x28000
	s_cmp_ge_u32 s51, 0x28000
	s_cselect_b32 s51, s53, s51
	s_add_u32 s52, s49, 0x20000
	s_sub_u32 s53, s52, 0x28000
	s_cmp_ge_u32 s52, 0x28000
	s_cselect_b32 s52, s53, s52
	v_add3_u32 v133, v197, v132, s49
	v_add3_u32 v134, v197, v135, s50
	ds_read_b128 v[216:219], v134
	ds_read_b128 v[224:227], v133
	ds_read_b128 v[220:223], v134 offset:4096
	ds_read_b128 v[228:231], v133 offset:4096
	ds_read_b128 v[232:235], v133 offset:8192
	ds_read_b128 v[236:239], v133 offset:12288
	s_add_u32 s54, s4, 0x80
	s_addc_u32 s55, s5, 0
	v_lshl_add_u64 v[136:137], v[128:129], 0, s[54:55]
	v_lshl_add_u64 v[138:139], v[130:131], 0, s[4:5]
	s_waitcnt lgkmcnt(6)
	v_mfma_f32_32x32x16_bf16 v[112:127], v[164:167], v[172:175], v[112:127]
	s_add_u32 m0, s51, s48
	v_lshl_add_u64 v[140:141], v[138:139], 0, s[22:23]
	global_load_lds_dwordx4 v[140:141], off
	v_mfma_f32_32x32x16_bf16 v[96:111], v[168:171], v[172:175], v[96:111]
	s_add_u32 s53, s51, s48
	s_add_u32 m0, s53, 0x2000
	v_lshl_add_u64 v[140:141], v[138:139], 0, s[24:25]
	global_load_lds_dwordx4 v[140:141], off
	v_mfma_f32_32x32x16_bf16 v[80:95], v[164:167], v[176:179], v[80:95]
	s_add_u32 s53, s51, s48
	s_add_u32 m0, s53, 0x4000
	v_lshl_add_u64 v[140:141], v[138:139], 0, s[26:27]
	global_load_lds_dwordx4 v[140:141], off
	v_mfma_f32_32x32x16_bf16 v[64:79], v[168:171], v[176:179], v[64:79]
	s_add_u32 s53, s51, s48
	s_add_u32 m0, s53, 0x6000
	v_lshl_add_u64 v[140:141], v[138:139], 0, s[28:29]
	global_load_lds_dwordx4 v[140:141], off
	v_mfma_f32_32x32x16_bf16 v[48:63], v[164:167], v[180:183], v[48:63]
	s_add_u32 m0, s52, s48
	v_lshl_add_u64 v[140:141], v[136:137], 0, s[22:23]
	global_load_lds_dwordx4 v[140:141], off
	v_mfma_f32_32x32x16_bf16 v[32:47], v[168:171], v[180:183], v[32:47]
	s_add_u32 s53, s52, s48
	s_add_u32 m0, s53, 0x2000
	v_lshl_add_u64 v[140:141], v[136:137], 0, s[24:25]
	global_load_lds_dwordx4 v[140:141], off
	v_mfma_f32_32x32x16_bf16 v[16:31], v[164:167], v[212:215], v[16:31]
	s_add_u32 s53, s52, s48
	s_add_u32 m0, s53, 0x4000
	v_lshl_add_u64 v[140:141], v[136:137], 0, s[26:27]
	global_load_lds_dwordx4 v[140:141], off
	v_mfma_f32_32x32x16_bf16 v[0:15], v[168:171], v[212:215], v[0:15]
	s_add_u32 s53, s52, s48
	s_add_u32 m0, s53, 0x6000
	v_lshl_add_u64 v[140:141], v[136:137], 0, s[28:29]
	global_load_lds_dwordx4 v[140:141], off
	s_waitcnt lgkmcnt(0)
	v_add3_u32 v133, v198, v132, s49
	v_add3_u32 v134, v198, v135, s50
	v_mfma_f32_32x32x16_bf16 v[112:127], v[216:219], v[224:227], v[112:127]
	v_mfma_f32_32x32x16_bf16 v[96:111], v[220:223], v[224:227], v[96:111]
	v_mfma_f32_32x32x16_bf16 v[80:95], v[216:219], v[228:231], v[80:95]
	ds_read_b128 v[164:167], v134
	v_mfma_f32_32x32x16_bf16 v[64:79], v[220:223], v[228:231], v[64:79]
	ds_read_b128 v[172:175], v133
	v_mfma_f32_32x32x16_bf16 v[48:63], v[216:219], v[232:235], v[48:63]
	ds_read_b128 v[168:171], v134 offset:4096
	v_mfma_f32_32x32x16_bf16 v[32:47], v[220:223], v[232:235], v[32:47]
	ds_read_b128 v[176:179], v133 offset:4096
	v_mfma_f32_32x32x16_bf16 v[16:31], v[216:219], v[236:239], v[16:31]
	ds_read_b128 v[180:183], v133 offset:8192
	v_mfma_f32_32x32x16_bf16 v[0:15], v[220:223], v[236:239], v[0:15]
	ds_read_b128 v[212:215], v133 offset:12288
	s_waitcnt lgkmcnt(0)
	v_add3_u32 v133, v199, v132, s49
	v_add3_u32 v134, v199, v135, s50
	v_mfma_f32_32x32x16_bf16 v[112:127], v[164:167], v[172:175], v[112:127]
	v_mfma_f32_32x32x16_bf16 v[96:111], v[168:171], v[172:175], v[96:111]
	v_mfma_f32_32x32x16_bf16 v[80:95], v[164:167], v[176:179], v[80:95]
	ds_read_b128 v[216:219], v134
	v_mfma_f32_32x32x16_bf16 v[64:79], v[168:171], v[176:179], v[64:79]
	ds_read_b128 v[224:227], v133
	v_mfma_f32_32x32x16_bf16 v[48:63], v[164:167], v[180:183], v[48:63]
	ds_read_b128 v[220:223], v134 offset:4096
	v_mfma_f32_32x32x16_bf16 v[32:47], v[168:171], v[180:183], v[32:47]
	ds_read_b128 v[228:231], v133 offset:4096
	v_mfma_f32_32x32x16_bf16 v[16:31], v[164:167], v[212:215], v[16:31]
	ds_read_b128 v[232:235], v133 offset:8192
	v_mfma_f32_32x32x16_bf16 v[0:15], v[168:171], v[212:215], v[0:15]
	ds_read_b128 v[236:239], v133 offset:12288
	s_waitcnt lgkmcnt(0)
	v_mfma_f32_32x32x16_bf16 v[112:127], v[216:219], v[224:227], v[112:127]
	v_mfma_f32_32x32x16_bf16 v[96:111], v[220:223], v[224:227], v[96:111]
	v_mfma_f32_32x32x16_bf16 v[80:95], v[216:219], v[228:231], v[80:95]
	v_mfma_f32_32x32x16_bf16 v[64:79], v[220:223], v[228:231], v[64:79]
	s_add_u32 s4, s4, 0x80
	s_addc_u32 s5, s5, 0
	s_add_u32 s49, s49, 0x10000
	s_sub_u32 s53, s49, 0x28000
	s_cmp_ge_u32 s49, 0x28000
	s_cselect_b32 s49, s53, s49
	s_mov_b32 s50, s51
	s_waitcnt vmcnt(4)
	s_barrier
	v_add3_u32 v133, v193, v132, s49
	v_add3_u32 v134, v193, v135, s50
	ds_read_b128 v[164:167], v134
	ds_read_b128 v[172:175], v133
	ds_read_b128 v[168:171], v134 offset:4096
	ds_read_b128 v[176:179], v133 offset:4096
	ds_read_b128 v[180:183], v133 offset:8192
	ds_read_b128 v[212:215], v133 offset:12288
	v_mfma_f32_32x32x16_bf16 v[48:63], v[216:219], v[232:235], v[48:63]
	v_mfma_f32_32x32x16_bf16 v[32:47], v[220:223], v[232:235], v[32:47]
	v_mfma_f32_32x32x16_bf16 v[16:31], v[216:219], v[236:239], v[16:31]
	v_mfma_f32_32x32x16_bf16 v[0:15], v[220:223], v[236:239], v[0:15]
	s_cmpk_lg_i32 s4, 0xf00
	s_cbranch_scc1 .Lgr1_loop
	s_add_u32 s51, s50, 0x10000
	s_sub_u32 s53, s51, 0x28000
	s_cmp_ge_u32 s51, 0x28000
	s_cselect_b32 s51, s53, s51
	v_add3_u32 v133, v197, v132, s49
	v_add3_u32 v134, v197, v135, s50
	ds_read_b128 v[216:219], v134
	ds_read_b128 v[224:227], v133
	ds_read_b128 v[220:223], v134 offset:4096
	ds_read_b128 v[228:231], v133 offset:4096
	ds_read_b128 v[232:235], v133 offset:8192
	ds_read_b128 v[236:239], v133 offset:12288
	s_add_u32 s54, s4, 0x80
	s_addc_u32 s55, s5, 0
	v_lshl_add_u64 v[136:137], v[128:129], 0, s[54:55]
	v_lshl_add_u64 v[138:139], v[130:131], 0, s[4:5]
	s_waitcnt lgkmcnt(6)
	v_mfma_f32_32x32x16_bf16 v[112:127], v[164:167], v[172:175], v[112:127]
	s_add_u32 m0, s51, s48
	v_lshl_add_u64 v[140:141], v[138:139], 0, s[22:23]
	global_load_lds_dwordx4 v[140:141], off
	v_mfma_f32_32x32x16_bf16 v[96:111], v[168:171], v[172:175], v[96:111]
	s_add_u32 s53, s51, s48
	s_add_u32 m0, s53, 0x2000
	v_lshl_add_u64 v[140:141], v[138:139], 0, s[24:25]
	global_load_lds_dwordx4 v[140:141], off
	v_mfma_f32_32x32x16_bf16 v[80:95], v[164:167], v[176:179], v[80:95]
	s_add_u32 s53, s51, s48
	s_add_u32 m0, s53, 0x4000
	v_lshl_add_u64 v[140:141], v[138:139], 0, s[26:27]
	global_load_lds_dwordx4 v[140:141], off
	v_mfma_f32_32x32x16_bf16 v[64:79], v[168:171], v[176:179], v[64:79]
	s_add_u32 s53, s51, s48
	s_add_u32 m0, s53, 0x6000
	v_lshl_add_u64 v[140:141], v[138:139], 0, s[28:29]
	global_load_lds_dwordx4 v[140:141], off
	v_mfma_f32_32x32x16_bf16 v[48:63], v[164:167], v[180:183], v[48:63]
	v_mfma_f32_32x32x16_bf16 v[32:47], v[168:171], v[180:183], v[32:47]
	v_mfma_f32_32x32x16_bf16 v[16:31], v[164:167], v[212:215], v[16:31]
	v_mfma_f32_32x32x16_bf16 v[0:15], v[168:171], v[212:215], v[0:15]
	s_waitcnt lgkmcnt(0)
	v_add3_u32 v133, v198, v132, s49
	v_add3_u32 v134, v198, v135, s50
	v_mfma_f32_32x32x16_bf16 v[112:127], v[216:219], v[224:227], v[112:127]
	v_mfma_f32_32x32x16_bf16 v[96:111], v[220:223], v[224:227], v[96:111]
	v_mfma_f32_32x32x16_bf16 v[80:95], v[216:219], v[228:231], v[80:95]
	ds_read_b128 v[164:167], v134
	v_mfma_f32_32x32x16_bf16 v[64:79], v[220:223], v[228:231], v[64:79]
	ds_read_b128 v[172:175], v133
	v_mfma_f32_32x32x16_bf16 v[48:63], v[216:219], v[232:235], v[48:63]
	ds_read_b128 v[168:171], v134 offset:4096
	v_mfma_f32_32x32x16_bf16 v[32:47], v[220:223], v[232:235], v[32:47]
	ds_read_b128 v[176:179], v133 offset:4096
	v_mfma_f32_32x32x16_bf16 v[16:31], v[216:219], v[236:239], v[16:31]
	ds_read_b128 v[180:183], v133 offset:8192
	v_mfma_f32_32x32x16_bf16 v[0:15], v[220:223], v[236:239], v[0:15]
	ds_read_b128 v[212:215], v133 offset:12288
	s_waitcnt lgkmcnt(0)
	v_add3_u32 v133, v199, v132, s49
	v_add3_u32 v134, v199, v135, s50
	v_mfma_f32_32x32x16_bf16 v[112:127], v[164:167], v[172:175], v[112:127]
	v_mfma_f32_32x32x16_bf16 v[96:111], v[168:171], v[172:175], v[96:111]
	v_mfma_f32_32x32x16_bf16 v[80:95], v[164:167], v[176:179], v[80:95]
	ds_read_b128 v[216:219], v134
	v_mfma_f32_32x32x16_bf16 v[64:79], v[168:171], v[176:179], v[64:79]
	ds_read_b128 v[224:227], v133
	v_mfma_f32_32x32x16_bf16 v[48:63], v[164:167], v[180:183], v[48:63]
	ds_read_b128 v[220:223], v134 offset:4096
	v_mfma_f32_32x32x16_bf16 v[32:47], v[168:171], v[180:183], v[32:47]
	ds_read_b128 v[228:231], v133 offset:4096
	v_mfma_f32_32x32x16_bf16 v[16:31], v[164:167], v[212:215], v[16:31]
	ds_read_b128 v[232:235], v133 offset:8192
	v_mfma_f32_32x32x16_bf16 v[0:15], v[168:171], v[212:215], v[0:15]
	ds_read_b128 v[236:239], v133 offset:12288
	s_waitcnt lgkmcnt(0)
	v_mfma_f32_32x32x16_bf16 v[112:127], v[216:219], v[224:227], v[112:127]
	v_mfma_f32_32x32x16_bf16 v[96:111], v[220:223], v[224:227], v[96:111]
	v_mfma_f32_32x32x16_bf16 v[80:95], v[216:219], v[228:231], v[80:95]
	v_mfma_f32_32x32x16_bf16 v[64:79], v[220:223], v[228:231], v[64:79]
	s_add_u32 s4, s4, 0x80
	s_addc_u32 s5, s5, 0
	s_add_u32 s49, s49, 0x10000
	s_sub_u32 s53, s49, 0x28000
	s_cmp_ge_u32 s49, 0x28000
	s_cselect_b32 s49, s53, s49
	s_mov_b32 s50, s51
	s_waitcnt vmcnt(0)
	s_barrier
	v_add3_u32 v133, v193, v132, s49
	v_add3_u32 v134, v193, v135, s50
	ds_read_b128 v[164:167], v134
	ds_read_b128 v[172:175], v133
	ds_read_b128 v[168:171], v134 offset:4096
	ds_read_b128 v[176:179], v133 offset:4096
	ds_read_b128 v[180:183], v133 offset:8192
	ds_read_b128 v[212:215], v133 offset:12288
	v_mfma_f32_32x32x16_bf16 v[48:63], v[216:219], v[232:235], v[48:63]
	v_mfma_f32_32x32x16_bf16 v[32:47], v[220:223], v[232:235], v[32:47]
	v_mfma_f32_32x32x16_bf16 v[16:31], v[216:219], v[236:239], v[16:31]
	v_mfma_f32_32x32x16_bf16 v[0:15], v[220:223], v[236:239], v[0:15]
	v_add3_u32 v133, v197, v132, s49
	v_add3_u32 v134, v197, v135, s50
	ds_read_b128 v[216:219], v134
	ds_read_b128 v[224:227], v133
	ds_read_b128 v[220:223], v134 offset:4096
	ds_read_b128 v[228:231], v133 offset:4096
	ds_read_b128 v[232:235], v133 offset:8192
	ds_read_b128 v[236:239], v133 offset:12288
	s_waitcnt lgkmcnt(6)
	v_mfma_f32_32x32x16_bf16 v[112:127], v[164:167], v[172:175], v[112:127]
	v_mfma_f32_32x32x16_bf16 v[96:111], v[168:171], v[172:175], v[96:111]
	v_mfma_f32_32x32x16_bf16 v[80:95], v[164:167], v[176:179], v[80:95]
	v_mfma_f32_32x32x16_bf16 v[64:79], v[168:171], v[176:179], v[64:79]
	v_mfma_f32_32x32x16_bf16 v[48:63], v[164:167], v[180:183], v[48:63]
	v_mfma_f32_32x32x16_bf16 v[32:47], v[168:171], v[180:183], v[32:47]
	v_mfma_f32_32x32x16_bf16 v[16:31], v[164:167], v[212:215], v[16:31]
	v_mfma_f32_32x32x16_bf16 v[0:15], v[168:171], v[212:215], v[0:15]
	s_waitcnt lgkmcnt(0)
	v_add3_u32 v133, v198, v132, s49
	v_add3_u32 v134, v198, v135, s50
	v_mfma_f32_32x32x16_bf16 v[112:127], v[216:219], v[224:227], v[112:127]
	v_mfma_f32_32x32x16_bf16 v[96:111], v[220:223], v[224:227], v[96:111]
	v_mfma_f32_32x32x16_bf16 v[80:95], v[216:219], v[228:231], v[80:95]
	ds_read_b128 v[164:167], v134
	v_mfma_f32_32x32x16_bf16 v[64:79], v[220:223], v[228:231], v[64:79]
	ds_read_b128 v[172:175], v133
	v_mfma_f32_32x32x16_bf16 v[48:63], v[216:219], v[232:235], v[48:63]
	ds_read_b128 v[168:171], v134 offset:4096
	v_mfma_f32_32x32x16_bf16 v[32:47], v[220:223], v[232:235], v[32:47]
	ds_read_b128 v[176:179], v133 offset:4096
	v_mfma_f32_32x32x16_bf16 v[16:31], v[216:219], v[236:239], v[16:31]
	ds_read_b128 v[180:183], v133 offset:8192
	v_mfma_f32_32x32x16_bf16 v[0:15], v[220:223], v[236:239], v[0:15]
	ds_read_b128 v[212:215], v133 offset:12288
	s_waitcnt lgkmcnt(0)
	v_add3_u32 v133, v199, v132, s49
	v_add3_u32 v134, v199, v135, s50
	v_mfma_f32_32x32x16_bf16 v[112:127], v[164:167], v[172:175], v[112:127]
	v_mfma_f32_32x32x16_bf16 v[96:111], v[168:171], v[172:175], v[96:111]
	v_mfma_f32_32x32x16_bf16 v[80:95], v[164:167], v[176:179], v[80:95]
	ds_read_b128 v[216:219], v134
	v_mfma_f32_32x32x16_bf16 v[64:79], v[168:171], v[176:179], v[64:79]
	ds_read_b128 v[224:227], v133
	v_mfma_f32_32x32x16_bf16 v[48:63], v[164:167], v[180:183], v[48:63]
	ds_read_b128 v[220:223], v134 offset:4096
	v_mfma_f32_32x32x16_bf16 v[32:47], v[168:171], v[180:183], v[32:47]
	ds_read_b128 v[228:231], v133 offset:4096
	v_mfma_f32_32x32x16_bf16 v[16:31], v[164:167], v[212:215], v[16:31]
	ds_read_b128 v[232:235], v133 offset:8192
	v_mfma_f32_32x32x16_bf16 v[0:15], v[168:171], v[212:215], v[0:15]
	ds_read_b128 v[236:239], v133 offset:12288
	s_waitcnt vmcnt(0) lgkmcnt(0)
	s_barrier
	v_mfma_f32_32x32x16_bf16 v[112:127], v[216:219], v[224:227], v[112:127]
	v_mfma_f32_32x32x16_bf16 v[96:111], v[220:223], v[224:227], v[96:111]
	v_mfma_f32_32x32x16_bf16 v[80:95], v[216:219], v[228:231], v[80:95]
	v_mfma_f32_32x32x16_bf16 v[64:79], v[220:223], v[228:231], v[64:79]
	v_mfma_f32_32x32x16_bf16 v[48:63], v[216:219], v[232:235], v[48:63]
	v_mfma_f32_32x32x16_bf16 v[32:47], v[220:223], v[232:235], v[32:47]
	v_mfma_f32_32x32x16_bf16 v[16:31], v[216:219], v[236:239], v[16:31]
	v_mfma_f32_32x32x16_bf16 v[0:15], v[220:223], v[236:239], v[0:15]
	s_nop 15

.Lgr2_loop:
	s_add_u32 s51, s50, 0x10000
	s_sub_u32 s53, s51, 0x28000
	s_cmp_ge_u32 s51, 0x28000
	s_cselect_b32 s51, s53, s51
	s_add_u32 s52, s49, 0x20000
	s_sub_u32 s53, s52, 0x28000
	s_cmp_ge_u32 s52, 0x28000
	s_cselect_b32 s52, s53, s52
	v_add3_u32 v143, v157, v142, s49
	v_add3_u32 v144, v157, v145, s50
	ds_read_b128 v[212:215], v144
	ds_read_b128 v[220:223], v143
	ds_read_b128 v[216:219], v144 offset:4096
	ds_read_b128 v[224:227], v143 offset:4096
	ds_read_b128 v[228:231], v143 offset:8192
	ds_read_b128 v[232:235], v143 offset:12288
	s_add_u32 s54, s28, 0x80
	s_addc_u32 s55, s29, 0
	v_lshl_add_u64 v[166:167], v[138:139], 0, s[54:55]
	v_lshl_add_u64 v[168:169], v[140:141], 0, s[28:29]
	s_waitcnt lgkmcnt(6)
	v_mfma_f32_32x32x16_bf16 v[112:127], v[188:191], v[196:199], v[112:127]
	s_add_u32 m0, s51, s48
	v_lshl_add_u64 v[170:171], v[168:169], 0, s[18:19]
	global_load_lds_dwordx4 v[170:171], off
	v_mfma_f32_32x32x16_bf16 v[96:111], v[192:195], v[196:199], v[96:111]
	s_add_u32 s53, s51, s48
	s_add_u32 m0, s53, 0x2000
	v_lshl_add_u64 v[170:171], v[168:169], 0, s[20:21]
	global_load_lds_dwordx4 v[170:171], off
	v_mfma_f32_32x32x16_bf16 v[80:95], v[188:191], v[200:203], v[80:95]
	s_add_u32 s53, s51, s48
	s_add_u32 m0, s53, 0x4000
	v_lshl_add_u64 v[170:171], v[168:169], 0, s[22:23]
	global_load_lds_dwordx4 v[170:171], off
	v_mfma_f32_32x32x16_bf16 v[64:79], v[192:195], v[200:203], v[64:79]
	s_add_u32 s53, s51, s48
	s_add_u32 m0, s53, 0x6000
	v_lshl_add_u64 v[170:171], v[168:169], 0, s[24:25]
	global_load_lds_dwordx4 v[170:171], off
	v_mfma_f32_32x32x16_bf16 v[48:63], v[188:191], v[204:207], v[48:63]
	s_add_u32 m0, s52, s48
	v_lshl_add_u64 v[170:171], v[166:167], 0, s[18:19]
	global_load_lds_dwordx4 v[170:171], off
	v_mfma_f32_32x32x16_bf16 v[32:47], v[192:195], v[204:207], v[32:47]
	s_add_u32 s53, s52, s48
	s_add_u32 m0, s53, 0x2000
	v_lshl_add_u64 v[170:171], v[166:167], 0, s[20:21]
	global_load_lds_dwordx4 v[170:171], off
	v_mfma_f32_32x32x16_bf16 v[16:31], v[188:191], v[208:211], v[16:31]
	s_add_u32 s53, s52, s48
	s_add_u32 m0, s53, 0x4000
	v_lshl_add_u64 v[170:171], v[166:167], 0, s[22:23]
	global_load_lds_dwordx4 v[170:171], off
	v_mfma_f32_32x32x16_bf16 v[0:15], v[192:195], v[208:211], v[0:15]
	s_add_u32 s53, s52, s48
	s_add_u32 m0, s53, 0x6000
	v_lshl_add_u64 v[170:171], v[166:167], 0, s[24:25]
	global_load_lds_dwordx4 v[170:171], off
	s_waitcnt lgkmcnt(0)
	v_add3_u32 v143, v158, v142, s49
	v_add3_u32 v144, v158, v145, s50
	v_mfma_f32_32x32x16_bf16 v[112:127], v[212:215], v[220:223], v[112:127]
	v_mfma_f32_32x32x16_bf16 v[96:111], v[216:219], v[220:223], v[96:111]
	v_mfma_f32_32x32x16_bf16 v[80:95], v[212:215], v[224:227], v[80:95]
	ds_read_b128 v[188:191], v144
	v_mfma_f32_32x32x16_bf16 v[64:79], v[216:219], v[224:227], v[64:79]
	ds_read_b128 v[196:199], v143
	v_mfma_f32_32x32x16_bf16 v[48:63], v[212:215], v[228:231], v[48:63]
	ds_read_b128 v[192:195], v144 offset:4096
	v_mfma_f32_32x32x16_bf16 v[32:47], v[216:219], v[228:231], v[32:47]
	ds_read_b128 v[200:203], v143 offset:4096
	v_mfma_f32_32x32x16_bf16 v[16:31], v[212:215], v[232:235], v[16:31]
	ds_read_b128 v[204:207], v143 offset:8192
	v_mfma_f32_32x32x16_bf16 v[0:15], v[216:219], v[232:235], v[0:15]
	ds_read_b128 v[208:211], v143 offset:12288
	s_waitcnt lgkmcnt(0)
	v_add3_u32 v143, v159, v142, s49
	v_add3_u32 v144, v159, v145, s50
	v_mfma_f32_32x32x16_bf16 v[112:127], v[188:191], v[196:199], v[112:127]
	v_mfma_f32_32x32x16_bf16 v[96:111], v[192:195], v[196:199], v[96:111]
	v_mfma_f32_32x32x16_bf16 v[80:95], v[188:191], v[200:203], v[80:95]
	ds_read_b128 v[212:215], v144
	v_mfma_f32_32x32x16_bf16 v[64:79], v[192:195], v[200:203], v[64:79]
	ds_read_b128 v[220:223], v143
	v_mfma_f32_32x32x16_bf16 v[48:63], v[188:191], v[204:207], v[48:63]
	ds_read_b128 v[216:219], v144 offset:4096
	v_mfma_f32_32x32x16_bf16 v[32:47], v[192:195], v[204:207], v[32:47]
	ds_read_b128 v[224:227], v143 offset:4096
	v_mfma_f32_32x32x16_bf16 v[16:31], v[188:191], v[208:211], v[16:31]
	ds_read_b128 v[228:231], v143 offset:8192
	v_mfma_f32_32x32x16_bf16 v[0:15], v[192:195], v[208:211], v[0:15]
	ds_read_b128 v[232:235], v143 offset:12288
	s_waitcnt lgkmcnt(0)
	v_mfma_f32_32x32x16_bf16 v[112:127], v[212:215], v[220:223], v[112:127]
	v_mfma_f32_32x32x16_bf16 v[96:111], v[216:219], v[220:223], v[96:111]
	v_mfma_f32_32x32x16_bf16 v[80:95], v[212:215], v[224:227], v[80:95]
	v_mfma_f32_32x32x16_bf16 v[64:79], v[216:219], v[224:227], v[64:79]
	s_add_u32 s28, s28, 0x80
	s_addc_u32 s29, s29, 0
	s_add_u32 s49, s49, 0x10000
	s_sub_u32 s53, s49, 0x28000
	s_cmp_ge_u32 s49, 0x28000
	s_cselect_b32 s49, s53, s49
	s_mov_b32 s50, s51
	s_waitcnt vmcnt(4)
	s_barrier
	v_add3_u32 v143, v153, v142, s49
	v_add3_u32 v144, v153, v145, s50
	ds_read_b128 v[188:191], v144
	ds_read_b128 v[196:199], v143
	ds_read_b128 v[192:195], v144 offset:4096
	ds_read_b128 v[200:203], v143 offset:4096
	ds_read_b128 v[204:207], v143 offset:8192
	ds_read_b128 v[208:211], v143 offset:12288
	v_mfma_f32_32x32x16_bf16 v[48:63], v[212:215], v[228:231], v[48:63]
	v_mfma_f32_32x32x16_bf16 v[32:47], v[216:219], v[228:231], v[32:47]
	v_mfma_f32_32x32x16_bf16 v[16:31], v[212:215], v[232:235], v[16:31]
	v_mfma_f32_32x32x16_bf16 v[0:15], v[216:219], v[232:235], v[0:15]
	s_cmpk_lg_i32 s28, 0xf00
	s_cbranch_scc1 .Lgr2_loop
	s_add_u32 s51, s50, 0x10000
	s_sub_u32 s53, s51, 0x28000
	s_cmp_ge_u32 s51, 0x28000
	s_cselect_b32 s51, s53, s51
	v_add3_u32 v143, v157, v142, s49
	v_add3_u32 v144, v157, v145, s50
	ds_read_b128 v[212:215], v144
	ds_read_b128 v[220:223], v143
	ds_read_b128 v[216:219], v144 offset:4096
	ds_read_b128 v[224:227], v143 offset:4096
	ds_read_b128 v[228:231], v143 offset:8192
	ds_read_b128 v[232:235], v143 offset:12288
	s_add_u32 s54, s28, 0x80
	s_addc_u32 s55, s29, 0
	v_lshl_add_u64 v[166:167], v[138:139], 0, s[54:55]
	v_lshl_add_u64 v[168:169], v[140:141], 0, s[28:29]
	s_waitcnt lgkmcnt(6)
	v_mfma_f32_32x32x16_bf16 v[112:127], v[188:191], v[196:199], v[112:127]
	s_add_u32 m0, s51, s48
	v_lshl_add_u64 v[170:171], v[168:169], 0, s[18:19]
	global_load_lds_dwordx4 v[170:171], off
	v_mfma_f32_32x32x16_bf16 v[96:111], v[192:195], v[196:199], v[96:111]
	s_add_u32 s53, s51, s48
	s_add_u32 m0, s53, 0x2000
	v_lshl_add_u64 v[170:171], v[168:169], 0, s[20:21]
	global_load_lds_dwordx4 v[170:171], off
	v_mfma_f32_32x32x16_bf16 v[80:95], v[188:191], v[200:203], v[80:95]
	s_add_u32 s53, s51, s48
	s_add_u32 m0, s53, 0x4000
	v_lshl_add_u64 v[170:171], v[168:169], 0, s[22:23]
	global_load_lds_dwordx4 v[170:171], off
	v_mfma_f32_32x32x16_bf16 v[64:79], v[192:195], v[200:203], v[64:79]
	s_add_u32 s53, s51, s48
	s_add_u32 m0, s53, 0x6000
	v_lshl_add_u64 v[170:171], v[168:169], 0, s[24:25]
	global_load_lds_dwordx4 v[170:171], off
	v_mfma_f32_32x32x16_bf16 v[48:63], v[188:191], v[204:207], v[48:63]
	v_mfma_f32_32x32x16_bf16 v[32:47], v[192:195], v[204:207], v[32:47]
	v_mfma_f32_32x32x16_bf16 v[16:31], v[188:191], v[208:211], v[16:31]
	v_mfma_f32_32x32x16_bf16 v[0:15], v[192:195], v[208:211], v[0:15]
	s_waitcnt lgkmcnt(0)
	v_add3_u32 v143, v158, v142, s49
	v_add3_u32 v144, v158, v145, s50
	v_mfma_f32_32x32x16_bf16 v[112:127], v[212:215], v[220:223], v[112:127]
	v_mfma_f32_32x32x16_bf16 v[96:111], v[216:219], v[220:223], v[96:111]
	v_mfma_f32_32x32x16_bf16 v[80:95], v[212:215], v[224:227], v[80:95]
	ds_read_b128 v[188:191], v144
	v_mfma_f32_32x32x16_bf16 v[64:79], v[216:219], v[224:227], v[64:79]
	ds_read_b128 v[196:199], v143
	v_mfma_f32_32x32x16_bf16 v[48:63], v[212:215], v[228:231], v[48:63]
	ds_read_b128 v[192:195], v144 offset:4096
	v_mfma_f32_32x32x16_bf16 v[32:47], v[216:219], v[228:231], v[32:47]
	ds_read_b128 v[200:203], v143 offset:4096
	v_mfma_f32_32x32x16_bf16 v[16:31], v[212:215], v[232:235], v[16:31]
	ds_read_b128 v[204:207], v143 offset:8192
	v_mfma_f32_32x32x16_bf16 v[0:15], v[216:219], v[232:235], v[0:15]
	ds_read_b128 v[208:211], v143 offset:12288
	s_waitcnt lgkmcnt(0)
	v_add3_u32 v143, v159, v142, s49
	v_add3_u32 v144, v159, v145, s50
	v_mfma_f32_32x32x16_bf16 v[112:127], v[188:191], v[196:199], v[112:127]
	v_mfma_f32_32x32x16_bf16 v[96:111], v[192:195], v[196:199], v[96:111]
	v_mfma_f32_32x32x16_bf16 v[80:95], v[188:191], v[200:203], v[80:95]
	ds_read_b128 v[212:215], v144
	v_mfma_f32_32x32x16_bf16 v[64:79], v[192:195], v[200:203], v[64:79]
	ds_read_b128 v[220:223], v143
	v_mfma_f32_32x32x16_bf16 v[48:63], v[188:191], v[204:207], v[48:63]
	ds_read_b128 v[216:219], v144 offset:4096
	v_mfma_f32_32x32x16_bf16 v[32:47], v[192:195], v[204:207], v[32:47]
	ds_read_b128 v[224:227], v143 offset:4096
	v_mfma_f32_32x32x16_bf16 v[16:31], v[188:191], v[208:211], v[16:31]
	ds_read_b128 v[228:231], v143 offset:8192
	v_mfma_f32_32x32x16_bf16 v[0:15], v[192:195], v[208:211], v[0:15]
	ds_read_b128 v[232:235], v143 offset:12288
	s_waitcnt lgkmcnt(0)
	v_mfma_f32_32x32x16_bf16 v[112:127], v[212:215], v[220:223], v[112:127]
	v_mfma_f32_32x32x16_bf16 v[96:111], v[216:219], v[220:223], v[96:111]
	v_mfma_f32_32x32x16_bf16 v[80:95], v[212:215], v[224:227], v[80:95]
	v_mfma_f32_32x32x16_bf16 v[64:79], v[216:219], v[224:227], v[64:79]
	s_add_u32 s28, s28, 0x80
	s_addc_u32 s29, s29, 0
	s_add_u32 s49, s49, 0x10000
	s_sub_u32 s53, s49, 0x28000
	s_cmp_ge_u32 s49, 0x28000
	s_cselect_b32 s49, s53, s49
	s_mov_b32 s50, s51
	s_waitcnt vmcnt(0)
	s_barrier
	v_add3_u32 v143, v153, v142, s49
	v_add3_u32 v144, v153, v145, s50
	ds_read_b128 v[188:191], v144
	ds_read_b128 v[196:199], v143
	ds_read_b128 v[192:195], v144 offset:4096
	ds_read_b128 v[200:203], v143 offset:4096
	ds_read_b128 v[204:207], v143 offset:8192
	ds_read_b128 v[208:211], v143 offset:12288
	v_mfma_f32_32x32x16_bf16 v[48:63], v[212:215], v[228:231], v[48:63]
	v_mfma_f32_32x32x16_bf16 v[32:47], v[216:219], v[228:231], v[32:47]
	v_mfma_f32_32x32x16_bf16 v[16:31], v[212:215], v[232:235], v[16:31]
	v_mfma_f32_32x32x16_bf16 v[0:15], v[216:219], v[232:235], v[0:15]
	v_add3_u32 v143, v157, v142, s49
	v_add3_u32 v144, v157, v145, s50
	ds_read_b128 v[212:215], v144
	ds_read_b128 v[220:223], v143
	ds_read_b128 v[216:219], v144 offset:4096
	ds_read_b128 v[224:227], v143 offset:4096
	ds_read_b128 v[228:231], v143 offset:8192
	ds_read_b128 v[232:235], v143 offset:12288
	s_waitcnt lgkmcnt(6)
	v_mfma_f32_32x32x16_bf16 v[112:127], v[188:191], v[196:199], v[112:127]
	v_mfma_f32_32x32x16_bf16 v[96:111], v[192:195], v[196:199], v[96:111]
	v_mfma_f32_32x32x16_bf16 v[80:95], v[188:191], v[200:203], v[80:95]
	v_mfma_f32_32x32x16_bf16 v[64:79], v[192:195], v[200:203], v[64:79]
	v_mfma_f32_32x32x16_bf16 v[48:63], v[188:191], v[204:207], v[48:63]
	v_mfma_f32_32x32x16_bf16 v[32:47], v[192:195], v[204:207], v[32:47]
	v_mfma_f32_32x32x16_bf16 v[16:31], v[188:191], v[208:211], v[16:31]
	v_mfma_f32_32x32x16_bf16 v[0:15], v[192:195], v[208:211], v[0:15]
	s_waitcnt lgkmcnt(0)
	v_add3_u32 v143, v158, v142, s49
	v_add3_u32 v144, v158, v145, s50
	v_mfma_f32_32x32x16_bf16 v[112:127], v[212:215], v[220:223], v[112:127]
	v_mfma_f32_32x32x16_bf16 v[96:111], v[216:219], v[220:223], v[96:111]
	v_mfma_f32_32x32x16_bf16 v[80:95], v[212:215], v[224:227], v[80:95]
	ds_read_b128 v[188:191], v144
	v_mfma_f32_32x32x16_bf16 v[64:79], v[216:219], v[224:227], v[64:79]
	ds_read_b128 v[196:199], v143
	v_mfma_f32_32x32x16_bf16 v[48:63], v[212:215], v[228:231], v[48:63]
	ds_read_b128 v[192:195], v144 offset:4096
	v_mfma_f32_32x32x16_bf16 v[32:47], v[216:219], v[228:231], v[32:47]
	ds_read_b128 v[200:203], v143 offset:4096
	v_mfma_f32_32x32x16_bf16 v[16:31], v[212:215], v[232:235], v[16:31]
	ds_read_b128 v[204:207], v143 offset:8192
	v_mfma_f32_32x32x16_bf16 v[0:15], v[216:219], v[232:235], v[0:15]
	ds_read_b128 v[208:211], v143 offset:12288
	s_waitcnt lgkmcnt(0)
	v_add3_u32 v143, v159, v142, s49
	v_add3_u32 v144, v159, v145, s50
	v_mfma_f32_32x32x16_bf16 v[112:127], v[188:191], v[196:199], v[112:127]
	v_mfma_f32_32x32x16_bf16 v[96:111], v[192:195], v[196:199], v[96:111]
	v_mfma_f32_32x32x16_bf16 v[80:95], v[188:191], v[200:203], v[80:95]
	ds_read_b128 v[212:215], v144
	v_mfma_f32_32x32x16_bf16 v[64:79], v[192:195], v[200:203], v[64:79]
	ds_read_b128 v[220:223], v143
	v_mfma_f32_32x32x16_bf16 v[48:63], v[188:191], v[204:207], v[48:63]
	ds_read_b128 v[216:219], v144 offset:4096
	v_mfma_f32_32x32x16_bf16 v[32:47], v[192:195], v[204:207], v[32:47]
	ds_read_b128 v[224:227], v143 offset:4096
	v_mfma_f32_32x32x16_bf16 v[16:31], v[188:191], v[208:211], v[16:31]
	ds_read_b128 v[228:231], v143 offset:8192
	v_mfma_f32_32x32x16_bf16 v[0:15], v[192:195], v[208:211], v[0:15]
	ds_read_b128 v[232:235], v143 offset:12288
	s_waitcnt vmcnt(0) lgkmcnt(0)
	s_barrier
	v_mfma_f32_32x32x16_bf16 v[112:127], v[212:215], v[220:223], v[112:127]
	v_mfma_f32_32x32x16_bf16 v[96:111], v[216:219], v[220:223], v[96:111]
	v_mfma_f32_32x32x16_bf16 v[80:95], v[212:215], v[224:227], v[80:95]
	v_mfma_f32_32x32x16_bf16 v[64:79], v[216:219], v[224:227], v[64:79]
	v_mfma_f32_32x32x16_bf16 v[48:63], v[212:215], v[228:231], v[48:63]
	v_mfma_f32_32x32x16_bf16 v[32:47], v[216:219], v[228:231], v[32:47]
	v_mfma_f32_32x32x16_bf16 v[16:31], v[212:215], v[232:235], v[16:31]
	v_mfma_f32_32x32x16_bf16 v[0:15], v[216:219], v[232:235], v[0:15]
	s_nop 15
	s_branch .LBB0_163

.Lgr3_loop:
	s_add_u32 s51, s50, 0x10000
	s_sub_u32 s53, s51, 0x28000
	s_cmp_ge_u32 s51, 0x28000
	s_cselect_b32 s51, s53, s51
	s_add_u32 s52, s49, 0x20000
	s_sub_u32 s53, s52, 0x28000
	s_cmp_ge_u32 s52, 0x28000
	s_cselect_b32 s52, s53, s52
	v_add3_u32 v241, v151, v240, s49
	v_add3_u32 v243, v151, v244, s50
	ds_read_b128 v[216:219], v243
	ds_read_b128 v[224:227], v241
	ds_read_b128 v[220:223], v243 offset:4096
	ds_read_b128 v[228:231], v241 offset:4096
	ds_read_b128 v[232:235], v241 offset:8192
	ds_read_b128 v[236:239], v241 offset:12288
	s_add_u32 s54, s28, 0x80
	s_addc_u32 s55, s29, 0
	v_lshl_add_u64 v[246:247], v[138:139], 0, s[54:55]
	v_lshl_add_u64 v[248:249], v[140:141], 0, s[28:29]
	s_waitcnt lgkmcnt(6)
	v_mfma_f32_32x32x16_bf16 v[112:127], v[192:195], v[200:203], v[112:127]
	s_add_u32 m0, s51, s48
	v_lshl_add_u64 v[250:251], v[248:249], 0, s[18:19]
	global_load_lds_dwordx4 v[250:251], off
	v_mfma_f32_32x32x16_bf16 v[96:111], v[196:199], v[200:203], v[96:111]
	s_add_u32 s53, s51, s48
	s_add_u32 m0, s53, 0x2000
	v_lshl_add_u64 v[250:251], v[248:249], 0, s[20:21]
	global_load_lds_dwordx4 v[250:251], off
	v_mfma_f32_32x32x16_bf16 v[80:95], v[192:195], v[204:207], v[80:95]
	s_add_u32 s53, s51, s48
	s_add_u32 m0, s53, 0x4000
	v_lshl_add_u64 v[250:251], v[248:249], 0, s[22:23]
	global_load_lds_dwordx4 v[250:251], off
	v_mfma_f32_32x32x16_bf16 v[64:79], v[196:199], v[204:207], v[64:79]
	s_add_u32 s53, s51, s48
	s_add_u32 m0, s53, 0x6000
	v_lshl_add_u64 v[250:251], v[248:249], 0, s[24:25]
	global_load_lds_dwordx4 v[250:251], off
	v_mfma_f32_32x32x16_bf16 v[48:63], v[192:195], v[208:211], v[48:63]
	s_add_u32 m0, s52, s48
	v_lshl_add_u64 v[250:251], v[246:247], 0, s[18:19]
	global_load_lds_dwordx4 v[250:251], off
	v_mfma_f32_32x32x16_bf16 v[32:47], v[196:199], v[208:211], v[32:47]
	s_add_u32 s53, s52, s48
	s_add_u32 m0, s53, 0x2000
	v_lshl_add_u64 v[250:251], v[246:247], 0, s[20:21]
	global_load_lds_dwordx4 v[250:251], off
	v_mfma_f32_32x32x16_bf16 v[16:31], v[192:195], v[212:215], v[16:31]
	s_add_u32 s53, s52, s48
	s_add_u32 m0, s53, 0x4000
	v_lshl_add_u64 v[250:251], v[246:247], 0, s[22:23]
	global_load_lds_dwordx4 v[250:251], off
	v_mfma_f32_32x32x16_bf16 v[0:15], v[196:199], v[212:215], v[0:15]
	s_add_u32 s53, s52, s48
	s_add_u32 m0, s53, 0x6000
	v_lshl_add_u64 v[250:251], v[246:247], 0, s[24:25]
	global_load_lds_dwordx4 v[250:251], off
	s_waitcnt lgkmcnt(0)
	v_add3_u32 v241, v152, v240, s49
	v_add3_u32 v243, v152, v244, s50
	v_mfma_f32_32x32x16_bf16 v[112:127], v[216:219], v[224:227], v[112:127]
	v_mfma_f32_32x32x16_bf16 v[96:111], v[220:223], v[224:227], v[96:111]
	v_mfma_f32_32x32x16_bf16 v[80:95], v[216:219], v[228:231], v[80:95]
	ds_read_b128 v[192:195], v243
	v_mfma_f32_32x32x16_bf16 v[64:79], v[220:223], v[228:231], v[64:79]
	ds_read_b128 v[200:203], v241
	v_mfma_f32_32x32x16_bf16 v[48:63], v[216:219], v[232:235], v[48:63]
	ds_read_b128 v[196:199], v243 offset:4096
	v_mfma_f32_32x32x16_bf16 v[32:47], v[220:223], v[232:235], v[32:47]
	ds_read_b128 v[204:207], v241 offset:4096
	v_mfma_f32_32x32x16_bf16 v[16:31], v[216:219], v[236:239], v[16:31]
	ds_read_b128 v[208:211], v241 offset:8192
	v_mfma_f32_32x32x16_bf16 v[0:15], v[220:223], v[236:239], v[0:15]
	ds_read_b128 v[212:215], v241 offset:12288
	s_waitcnt lgkmcnt(0)
	v_add3_u32 v241, v153, v240, s49
	v_add3_u32 v243, v153, v244, s50
	v_mfma_f32_32x32x16_bf16 v[112:127], v[192:195], v[200:203], v[112:127]
	v_mfma_f32_32x32x16_bf16 v[96:111], v[196:199], v[200:203], v[96:111]
	v_mfma_f32_32x32x16_bf16 v[80:95], v[192:195], v[204:207], v[80:95]
	ds_read_b128 v[216:219], v243
	v_mfma_f32_32x32x16_bf16 v[64:79], v[196:199], v[204:207], v[64:79]
	ds_read_b128 v[224:227], v241
	v_mfma_f32_32x32x16_bf16 v[48:63], v[192:195], v[208:211], v[48:63]
	ds_read_b128 v[220:223], v243 offset:4096
	v_mfma_f32_32x32x16_bf16 v[32:47], v[196:199], v[208:211], v[32:47]
	ds_read_b128 v[228:231], v241 offset:4096
	v_mfma_f32_32x32x16_bf16 v[16:31], v[192:195], v[212:215], v[16:31]
	ds_read_b128 v[232:235], v241 offset:8192
	v_mfma_f32_32x32x16_bf16 v[0:15], v[196:199], v[212:215], v[0:15]
	ds_read_b128 v[236:239], v241 offset:12288
	s_waitcnt lgkmcnt(0)
	v_mfma_f32_32x32x16_bf16 v[112:127], v[216:219], v[224:227], v[112:127]
	v_mfma_f32_32x32x16_bf16 v[96:111], v[220:223], v[224:227], v[96:111]
	v_mfma_f32_32x32x16_bf16 v[80:95], v[216:219], v[228:231], v[80:95]
	v_mfma_f32_32x32x16_bf16 v[64:79], v[220:223], v[228:231], v[64:79]
	s_add_u32 s28, s28, 0x80
	s_addc_u32 s29, s29, 0
	s_add_u32 s49, s49, 0x10000
	s_sub_u32 s53, s49, 0x28000
	s_cmp_ge_u32 s49, 0x28000
	s_cselect_b32 s49, s53, s49
	s_mov_b32 s50, s51
	s_waitcnt vmcnt(4)
	s_barrier
	v_add3_u32 v241, v147, v240, s49
	v_add3_u32 v243, v147, v244, s50
	ds_read_b128 v[192:195], v243
	ds_read_b128 v[200:203], v241
	ds_read_b128 v[196:199], v243 offset:4096
	ds_read_b128 v[204:207], v241 offset:4096
	ds_read_b128 v[208:211], v241 offset:8192
	ds_read_b128 v[212:215], v241 offset:12288
	v_mfma_f32_32x32x16_bf16 v[48:63], v[216:219], v[232:235], v[48:63]
	v_mfma_f32_32x32x16_bf16 v[32:47], v[220:223], v[232:235], v[32:47]
	v_mfma_f32_32x32x16_bf16 v[16:31], v[216:219], v[236:239], v[16:31]
	v_mfma_f32_32x32x16_bf16 v[0:15], v[220:223], v[236:239], v[0:15]
	s_cmpk_lg_i32 s28, 0xf00
	s_cbranch_scc1 .Lgr3_loop
	s_add_u32 s51, s50, 0x10000
	s_sub_u32 s53, s51, 0x28000
	s_cmp_ge_u32 s51, 0x28000
	s_cselect_b32 s51, s53, s51
	v_add3_u32 v241, v151, v240, s49
	v_add3_u32 v243, v151, v244, s50
	ds_read_b128 v[216:219], v243
	ds_read_b128 v[224:227], v241
	ds_read_b128 v[220:223], v243 offset:4096
	ds_read_b128 v[228:231], v241 offset:4096
	ds_read_b128 v[232:235], v241 offset:8192
	ds_read_b128 v[236:239], v241 offset:12288
	s_add_u32 s54, s28, 0x80
	s_addc_u32 s55, s29, 0
	v_lshl_add_u64 v[246:247], v[138:139], 0, s[54:55]
	v_lshl_add_u64 v[248:249], v[140:141], 0, s[28:29]
	s_waitcnt lgkmcnt(6)
	v_mfma_f32_32x32x16_bf16 v[112:127], v[192:195], v[200:203], v[112:127]
	s_add_u32 m0, s51, s48
	v_lshl_add_u64 v[250:251], v[248:249], 0, s[18:19]
	global_load_lds_dwordx4 v[250:251], off
	v_mfma_f32_32x32x16_bf16 v[96:111], v[196:199], v[200:203], v[96:111]
	s_add_u32 s53, s51, s48
	s_add_u32 m0, s53, 0x2000
	v_lshl_add_u64 v[250:251], v[248:249], 0, s[20:21]
	global_load_lds_dwordx4 v[250:251], off
	v_mfma_f32_32x32x16_bf16 v[80:95], v[192:195], v[204:207], v[80:95]
	s_add_u32 s53, s51, s48
	s_add_u32 m0, s53, 0x4000
	v_lshl_add_u64 v[250:251], v[248:249], 0, s[22:23]
	global_load_lds_dwordx4 v[250:251], off
	v_mfma_f32_32x32x16_bf16 v[64:79], v[196:199], v[204:207], v[64:79]
	s_add_u32 s53, s51, s48
	s_add_u32 m0, s53, 0x6000
	v_lshl_add_u64 v[250:251], v[248:249], 0, s[24:25]
	global_load_lds_dwordx4 v[250:251], off
	v_mfma_f32_32x32x16_bf16 v[48:63], v[192:195], v[208:211], v[48:63]
	v_mfma_f32_32x32x16_bf16 v[32:47], v[196:199], v[208:211], v[32:47]
	v_mfma_f32_32x32x16_bf16 v[16:31], v[192:195], v[212:215], v[16:31]
	v_mfma_f32_32x32x16_bf16 v[0:15], v[196:199], v[212:215], v[0:15]
	s_waitcnt lgkmcnt(0)
	v_add3_u32 v241, v152, v240, s49
	v_add3_u32 v243, v152, v244, s50
	v_mfma_f32_32x32x16_bf16 v[112:127], v[216:219], v[224:227], v[112:127]
	v_mfma_f32_32x32x16_bf16 v[96:111], v[220:223], v[224:227], v[96:111]
	v_mfma_f32_32x32x16_bf16 v[80:95], v[216:219], v[228:231], v[80:95]
	ds_read_b128 v[192:195], v243
	v_mfma_f32_32x32x16_bf16 v[64:79], v[220:223], v[228:231], v[64:79]
	ds_read_b128 v[200:203], v241
	v_mfma_f32_32x32x16_bf16 v[48:63], v[216:219], v[232:235], v[48:63]
	ds_read_b128 v[196:199], v243 offset:4096
	v_mfma_f32_32x32x16_bf16 v[32:47], v[220:223], v[232:235], v[32:47]
	ds_read_b128 v[204:207], v241 offset:4096
	v_mfma_f32_32x32x16_bf16 v[16:31], v[216:219], v[236:239], v[16:31]
	ds_read_b128 v[208:211], v241 offset:8192
	v_mfma_f32_32x32x16_bf16 v[0:15], v[220:223], v[236:239], v[0:15]
	ds_read_b128 v[212:215], v241 offset:12288
	s_waitcnt lgkmcnt(0)
	v_add3_u32 v241, v153, v240, s49
	v_add3_u32 v243, v153, v244, s50
	v_mfma_f32_32x32x16_bf16 v[112:127], v[192:195], v[200:203], v[112:127]
	v_mfma_f32_32x32x16_bf16 v[96:111], v[196:199], v[200:203], v[96:111]
	v_mfma_f32_32x32x16_bf16 v[80:95], v[192:195], v[204:207], v[80:95]
	ds_read_b128 v[216:219], v243
	v_mfma_f32_32x32x16_bf16 v[64:79], v[196:199], v[204:207], v[64:79]
	ds_read_b128 v[224:227], v241
	v_mfma_f32_32x32x16_bf16 v[48:63], v[192:195], v[208:211], v[48:63]
	ds_read_b128 v[220:223], v243 offset:4096
	v_mfma_f32_32x32x16_bf16 v[32:47], v[196:199], v[208:211], v[32:47]
	ds_read_b128 v[228:231], v241 offset:4096
	v_mfma_f32_32x32x16_bf16 v[16:31], v[192:195], v[212:215], v[16:31]
	ds_read_b128 v[232:235], v241 offset:8192
	v_mfma_f32_32x32x16_bf16 v[0:15], v[196:199], v[212:215], v[0:15]
	ds_read_b128 v[236:239], v241 offset:12288
	s_waitcnt lgkmcnt(0)
	v_mfma_f32_32x32x16_bf16 v[112:127], v[216:219], v[224:227], v[112:127]
	v_mfma_f32_32x32x16_bf16 v[96:111], v[220:223], v[224:227], v[96:111]
	v_mfma_f32_32x32x16_bf16 v[80:95], v[216:219], v[228:231], v[80:95]
	v_mfma_f32_32x32x16_bf16 v[64:79], v[220:223], v[228:231], v[64:79]
	s_add_u32 s28, s28, 0x80
	s_addc_u32 s29, s29, 0
	s_add_u32 s49, s49, 0x10000
	s_sub_u32 s53, s49, 0x28000
	s_cmp_ge_u32 s49, 0x28000
	s_cselect_b32 s49, s53, s49
	s_mov_b32 s50, s51
	s_waitcnt vmcnt(0)
	s_barrier
	v_add3_u32 v241, v147, v240, s49
	v_add3_u32 v243, v147, v244, s50
	ds_read_b128 v[192:195], v243
	ds_read_b128 v[200:203], v241
	ds_read_b128 v[196:199], v243 offset:4096
	ds_read_b128 v[204:207], v241 offset:4096
	ds_read_b128 v[208:211], v241 offset:8192
	ds_read_b128 v[212:215], v241 offset:12288
	v_mfma_f32_32x32x16_bf16 v[48:63], v[216:219], v[232:235], v[48:63]
	v_mfma_f32_32x32x16_bf16 v[32:47], v[220:223], v[232:235], v[32:47]
	v_mfma_f32_32x32x16_bf16 v[16:31], v[216:219], v[236:239], v[16:31]
	v_mfma_f32_32x32x16_bf16 v[0:15], v[220:223], v[236:239], v[0:15]
	v_add3_u32 v241, v151, v240, s49
	v_add3_u32 v243, v151, v244, s50
	ds_read_b128 v[216:219], v243
	ds_read_b128 v[224:227], v241
	ds_read_b128 v[220:223], v243 offset:4096
	ds_read_b128 v[228:231], v241 offset:4096
	ds_read_b128 v[232:235], v241 offset:8192
	ds_read_b128 v[236:239], v241 offset:12288
	s_waitcnt lgkmcnt(6)
	v_mfma_f32_32x32x16_bf16 v[112:127], v[192:195], v[200:203], v[112:127]
	v_mfma_f32_32x32x16_bf16 v[96:111], v[196:199], v[200:203], v[96:111]
	v_mfma_f32_32x32x16_bf16 v[80:95], v[192:195], v[204:207], v[80:95]
	v_mfma_f32_32x32x16_bf16 v[64:79], v[196:199], v[204:207], v[64:79]
	v_mfma_f32_32x32x16_bf16 v[48:63], v[192:195], v[208:211], v[48:63]
	v_mfma_f32_32x32x16_bf16 v[32:47], v[196:199], v[208:211], v[32:47]
	v_mfma_f32_32x32x16_bf16 v[16:31], v[192:195], v[212:215], v[16:31]
	v_mfma_f32_32x32x16_bf16 v[0:15], v[196:199], v[212:215], v[0:15]
	s_waitcnt lgkmcnt(0)
	v_add3_u32 v241, v152, v240, s49
	v_add3_u32 v243, v152, v244, s50
	v_mfma_f32_32x32x16_bf16 v[112:127], v[216:219], v[224:227], v[112:127]
	v_mfma_f32_32x32x16_bf16 v[96:111], v[220:223], v[224:227], v[96:111]
	v_mfma_f32_32x32x16_bf16 v[80:95], v[216:219], v[228:231], v[80:95]
	ds_read_b128 v[192:195], v243
	v_mfma_f32_32x32x16_bf16 v[64:79], v[220:223], v[228:231], v[64:79]
	ds_read_b128 v[200:203], v241
	v_mfma_f32_32x32x16_bf16 v[48:63], v[216:219], v[232:235], v[48:63]
	ds_read_b128 v[196:199], v243 offset:4096
	v_mfma_f32_32x32x16_bf16 v[32:47], v[220:223], v[232:235], v[32:47]
	ds_read_b128 v[204:207], v241 offset:4096
	v_mfma_f32_32x32x16_bf16 v[16:31], v[216:219], v[236:239], v[16:31]
	ds_read_b128 v[208:211], v241 offset:8192
	v_mfma_f32_32x32x16_bf16 v[0:15], v[220:223], v[236:239], v[0:15]
	ds_read_b128 v[212:215], v241 offset:12288
	s_waitcnt lgkmcnt(0)
	v_add3_u32 v241, v153, v240, s49
	v_add3_u32 v243, v153, v244, s50
	v_mfma_f32_32x32x16_bf16 v[112:127], v[192:195], v[200:203], v[112:127]
	v_mfma_f32_32x32x16_bf16 v[96:111], v[196:199], v[200:203], v[96:111]
	v_mfma_f32_32x32x16_bf16 v[80:95], v[192:195], v[204:207], v[80:95]
	ds_read_b128 v[216:219], v243
	v_mfma_f32_32x32x16_bf16 v[64:79], v[196:199], v[204:207], v[64:79]
	ds_read_b128 v[224:227], v241
	v_mfma_f32_32x32x16_bf16 v[48:63], v[192:195], v[208:211], v[48:63]
	ds_read_b128 v[220:223], v243 offset:4096
	v_mfma_f32_32x32x16_bf16 v[32:47], v[196:199], v[208:211], v[32:47]
	ds_read_b128 v[228:231], v241 offset:4096
	v_mfma_f32_32x32x16_bf16 v[16:31], v[192:195], v[212:215], v[16:31]
	ds_read_b128 v[232:235], v241 offset:8192
	v_mfma_f32_32x32x16_bf16 v[0:15], v[196:199], v[212:215], v[0:15]
	ds_read_b128 v[236:239], v241 offset:12288
	s_waitcnt vmcnt(0) lgkmcnt(0)
	s_barrier
	v_mfma_f32_32x32x16_bf16 v[112:127], v[216:219], v[224:227], v[112:127]
	v_mfma_f32_32x32x16_bf16 v[96:111], v[220:223], v[224:227], v[96:111]
	v_mfma_f32_32x32x16_bf16 v[80:95], v[216:219], v[228:231], v[80:95]
	v_mfma_f32_32x32x16_bf16 v[64:79], v[220:223], v[228:231], v[64:79]
	v_mfma_f32_32x32x16_bf16 v[48:63], v[216:219], v[232:235], v[48:63]
	v_mfma_f32_32x32x16_bf16 v[32:47], v[220:223], v[232:235], v[32:47]
	v_mfma_f32_32x32x16_bf16 v[16:31], v[216:219], v[236:239], v[16:31]
	v_mfma_f32_32x32x16_bf16 v[0:15], v[220:223], v[236:239], v[0:15]
	s_nop 15

.LBB0_217:
	s_or_b64 exec, exec, s[4:5]
	s_barrier
	v_readlane_b32 s2, v242, 0
	v_ashrrev_i32_e32 v0, 6, v186
	s_nop 0
	v_add_u32_e32 v0, s2, v0
	s_nop 0
	v_readfirstlane_b32 s4, v0
	s_mov_b32 s5, s76
	s_cmpk_gt_i32 s4, 0x3fff
	s_cbranch_scc1 .LBB0_226
	s_load_dwordx2 s[28:29], s[0:1], 0xb0
	s_load_dwordx2 s[26:27], s[0:1], 0xc0
	s_load_dwordx4 s[16:19], s[0:1], 0xf0
	s_load_dwordx2 s[10:11], s[0:1], 0x100
	s_load_dwordx4 s[20:23], s[0:1], 0x108
	s_load_dwordx4 s[12:15], s[0:1], 0x148
	s_load_dwordx2 s[24:25], s[0:1], 0x158
	v_and_b32_e32 v228, 63, v186
	v_and_b32_e32 v212, 7, v228
	v_lshrrev_b32_e32 v213, 3, v228
	v_lshlrev_b32_e32 v220, 4, v212
	v_lshlrev_b32_e32 v224, 3, v212
	v_sub_u32_e32 v221, 0x80, v224
	v_bfrev_b32_e32 v214, v213
	v_lshrrev_b32_e32 v214, 29, v214
	v_lshl_add_u32 v225, v214, 9, v224
	v_lshl_add_u32 v226, v214, 10, v220
	v_xor_b32_e32 v227, 32, v228
	v_lshlrev_b32_e32 v227, 2, v227
	v_mov_b32_e32 v231, 0
	v_lshrrev_b32_e32 v215, 6, v186
	s_nop 0
	v_readfirstlane_b32 s64, v215
	s_lshl_b32 s64, s64, 13
	s_add_i32 s64, s64, 16
	v_lshl_add_u32 v222, v228, 3, s64
	v_lshl_add_u32 v223, v213, 6, s64
	v_lshl_add_u32 v230, v228, 2, s64
	v_add_u32_e32 v229, 0x1000, v223
	s_mov_b32 s40, 0xaaaaaaaa
	s_mov_b32 s41, 0xaaaaaaaa
	s_mov_b32 s42, 0xcccccccc
	s_mov_b32 s43, 0xcccccccc
	s_mov_b32 s44, 0xf0f0f0f0
	s_mov_b32 s45, 0xf0f0f0f0
	s_mov_b32 s46, 0xff00ff00
	s_mov_b32 s47, 0xff00ff00
	s_mov_b32 s48, 0xffff0000
	s_mov_b32 s49, 0xffff0000
	s_mov_b32 s50, 0
	s_mov_b32 s51, -1
	s_movk_i32 s52, 0xc0
	s_mov_b32 s66, 0x378e98ab
	s_mov_b32 s67, 0xb9c68948
	s_mov_b32 s68, 0x3b7cd369
	s_mov_b32 s69, 0xbcc618b2
	s_mov_b32 s70, 0x3dda74e4
	s_mov_b32 s71, 0x3f228afd
	s_mov_b32 s72, 0x3e03c728
	s_mov_b32 s73, 0xbfb8aa3b
	s_mov_b32 s74, 0x42ce8ed0
	s_mov_b32 s75, 0xc2b17218
	s_mov_b32 s76, 0x3ba10414
	s_mov_b32 s77, 0x7fffffff
	s_lshr_b32 s91, s64, 13
	s_mov_b32 s6, s4
	s_waitcnt lgkmcnt(0)
